# grid barrier: last top-level arriver bumps every XCD's generation word itself; followers poll their XCD-local word
# baseline (speedup 1.0000x reference)
.LBB0_718:
	flat_atomic_add v[0:1], v185
	s_add_u32 s98, s6, 0x2400
	s_addc_u32 s99, s7, 0
	v_mov_b64_e32 v[2:3], s[98:99]
	flat_atomic_add v[2:3], v185
	flat_atomic_add v[2:3], v185 offset:256
	flat_atomic_add v[2:3], v185 offset:512
	flat_atomic_add v[2:3], v185 offset:768
	flat_atomic_add v[2:3], v185 offset:1024
	flat_atomic_add v[2:3], v185 offset:1280
	flat_atomic_add v[2:3], v185 offset:1536
	flat_atomic_add v[2:3], v185 offset:1792
	flat_atomic_add v[2:3], v185 offset:2048
	flat_atomic_add v[2:3], v185 offset:2304
	flat_atomic_add v[2:3], v185 offset:2560
	flat_atomic_add v[2:3], v185 offset:2816
	flat_atomic_add v[2:3], v185 offset:3072
	flat_atomic_add v[2:3], v185 offset:3328
	flat_atomic_add v[2:3], v185 offset:3584
	flat_atomic_add v[2:3], v185 offset:3840
	s_getpc_b64 s[98:99]
